# P6 column-tile order reversed so its last round writes the U columns P7 reads first (L2-resident)
# speedup vs baseline: 1.0142x; 1.0142x over previous
; #define PG8_BAR __builtin_amdgcn_s_barrier()
;     __host__ __device__ bool at(long L, Unit& u) const {
;         if (L >= nwg) return false;
;         int wgid = (int)L; { const int q = nwg / NXCD, r = nwg % NXCD, xcd = wgid % NXCD, off = wgid / NXCD; wgid = (xcd < r ? xcd * (q + 1) : r * (q + 1) + (xcd - r) * q) + off; }
;         const int nig = WGM * nN, gid = wgid / nig, fm = gid * WGM, gsz = (nM - fm) < WGM ? (nM - fm) : WGM;
;         u.pm = fm + ((wgid % nig) % gsz); u.pn = (wgid % nig) / gsz; u.k0 = 0; u.nt = ntk; return true;
;     const int tid = tid_of(wave0), wid = wave0, lane = tid & 63, wr = wid >> 2, wc = wid & 3, fr = lane & 15, fq = lane >> 4;
;     const int K = g.K;
;     unsigned voffA[2], voffB[2];
; #pragma unroll
;     for (int i = 0; i < 2; ++i) { int R, C; stage_rc(tid * 16 + i * 8192, R, C); const int Rb = (R >> 5) * 64 + (Epi::PERM ? perm32(R & 31) : (R & 31));
;         voffA[i] = (unsigned)(R * K + C) * 2u; voffB[i] = (unsigned)(Rb * K + C) * 2u; }
;     const size_t kstep = (size_t)(BK * 2);
;     const size_t hstep = (size_t)HALF * K * 2;
;     const size_t tstep = 2 * hstep;
;     const size_t hstepB = (size_t)32 * K * 2;
;     const unsigned ldsw = (unsigned)wid * 1024u;
;     const int aoff = lds_byte(wr * 64 + fr, fq * 8), boff = lds_byte(wc * 32 + fr, fq * 8);
;     ...
;     Unit cur, nxt; int ui = 0;
;     if (!S.next(0, cur)) return;
;     f32x4 acc[2][2][4][2];
; #pragma unroll
;     for (int a = 0; a < 2; ++a)
; #pragma unroll
;         for (int b = 0; b < 2; ++b)
; #pragma unroll
;             for (int m = 0; m < 4; ++m)
; #pragma unroll
;                 for (int n = 0; n < 2; ++n) acc[a][b][m][n] = (f32x4){0.f, 0.f, 0.f, 0.f};
;     bf16x8 At[4][2], B0[2][2], B1[2][2];
;     const char* cA = (const char*)g.A + (size_t)cur.pm * tstep + (size_t)cur.k0 * (BK * 2); const char* cB = (const char*)g.Bt + (size_t)cur.pn * tstep + (size_t)cur.k0 * (BK * 2);
;     S.a_ready(cur);
;     if constexpr (SP2) {
;         PG8_STAGE(PG8_SB(0, 0), cB, voffB); PG8_STAGE(PG8_SB(0, 1), cB + hstepB, voffB); PG8_STAGEA(PG8_SA(0, 0), cA, voffA); PG8_STAGEA(PG8_SA(0, 1), cA + hstep, voffA);
;         if (wr == 1) PG8_BAR;
;         PG8_WAIT_V(2); PG8_BAR;
;         PG8_STAGE(PG8_SB(1, 0), cB + kstep, voffB); PG8_STAGEA(PG8_SA(1, 0), cA + kstep, voffA); PG8_STAGE(PG8_SB(1, 1), cB + hstepB + kstep, voffB);
;         PG8_WAIT_V(6); PG8_BAR;
.LBB0_968:
	s_or_b64 exec, exec, s[0:1]
	s_lshl_b32 s12, s49, 4
	s_add_u32 s4, s68, 0x3200000
	s_addc_u32 s5, s69, 0
	v_mov_b32_e32 v10, v175
	s_cmp_ge_i32 s2, s12
	s_waitcnt lgkmcnt(0)
	s_barrier
	s_cbranch_scc1 .LBB0_984
	v_lshlrev_b32_e32 v0, 4, v10
	v_add_u32_e32 v1, 0x2000, v0
	v_ashrrev_i32_e32 v2, 31, v1
	v_lshrrev_b32_e32 v2, 22, v2
	v_add_u32_e32 v2, v1, v2
	v_ashrrev_i32_e32 v8, 10, v2
	v_mul_i32_i24_e32 v2, 0x400, v8
	v_sub_u32_e32 v1, v1, v2
	v_lshrrev_b32_e32 v2, 4, v1
	v_bitop3_b32 v1, v2, v1, 32 bitop3:0x6c
	v_ashrrev_i32_e32 v2, 31, v1
	v_lshrrev_b32_e32 v2, 26, v2
	v_add_u32_e32 v2, v1, v2
	v_lshlrev_b32_e32 v4, 3, v8
	v_ashrrev_i32_e32 v9, 6, v2
	v_and_b32_e32 v4, -16, v4
	v_add_u32_e32 v4, v9, v4
	v_lshrrev_b32_e32 v5, 2, v4
	v_lshlrev_b32_e32 v6, 1, v4
	v_and_b32_e32 v2, 0xc0, v2
	v_and_b32_e32 v3, 3, v9
	v_and_b32_e32 v5, 4, v5
	v_and_b32_e32 v6, 0x1fffd8, v6
	v_sub_u32_e32 v1, v1, v2
	v_mov_b32_e32 v2, 1
	v_or3_b32 v3, v3, v5, v6
	v_lshlrev_b32_e32 v5, 5, v8
	v_ashrrev_i16_sdwa v1, v2, sext(v1) dst_sel:DWORD dst_unused:UNUSED_PAD src0_sel:DWORD src1_sel:BYTE_0
	s_add_u32 s3, s68, 0xa00000
	v_and_b32_e32 v5, 32, v5
	v_bfe_i32 v11, v1, 0, 16
	s_addc_u32 s21, s69, 0
	v_add_lshl_u32 v1, v5, v11, 1
	s_ashr_i32 s44, s2, 31
	v_lshl_add_u32 v128, v3, 11, v1
	v_lshl_add_u32 v130, v4, 11, v1
	v_bfe_i32 v1, v10, 27, 1
	s_lshr_b32 s0, s44, 29
	v_lshrrev_b32_e32 v1, 22, v1
	s_add_i32 s0, s2, s0
	v_add_u32_e32 v1, v0, v1
	s_lshl_b32 s23, s49, 1
	s_ashr_i32 s1, s0, 3
	s_and_b32 s0, s0, -8
	v_and_b32_e32 v1, 0xfffffc00, v1
	s_sub_i32 s0, s2, s0
	s_or_b32 s45, s23, 1
	v_sub_u32_e32 v0, v0, v1
	v_ashrrev_i32_e32 v3, 31, v10
	s_cmp_lt_i32 s0, 0
	v_lshrrev_b32_e32 v1, 4, v0
	v_lshrrev_b32_e32 v3, 26, v3
	s_cselect_b32 s13, s45, s23
	v_bitop3_b32 v1, v1, v0, 32 bitop3:0x6c
	v_ashrrev_i32_e32 v0, 31, v0
	v_add_u32_e32 v3, v10, v3
	s_mul_i32 s0, s13, s0
	v_lshrrev_b32_e32 v0, 26, v0
	v_ashrrev_i32_e32 v13, 6, v3
	s_add_i32 s0, s0, s1
	v_add_u32_e32 v0, v1, v0
	v_lshlrev_b32_e32 v3, 3, v13
	s_ashr_i32 s1, s0, 31
	v_ashrrev_i32_e32 v12, 6, v0
	v_and_b32_e32 v3, -16, v3
	s_lshr_b32 s1, s1, 25
	v_add_u32_e32 v3, v12, v3
	s_add_i32 s1, s0, s1
	v_lshrrev_b32_e32 v4, 2, v3
	v_lshlrev_b32_e32 v5, 1, v3
	s_ashr_i32 s13, s1, 7
	v_and_b32_e32 v0, 3, v12
	v_and_b32_e32 v4, 4, v4
	v_and_b32_e32 v5, 0x1fffd8, v5
	s_lshl_b32 s13, s13, 3
	v_or3_b32 v0, v0, v4, v5
	v_mul_i32_i24_e32 v5, 64, v12
	s_sub_i32 s14, s49, s13
	v_sub_u32_e32 v1, v1, v5
	s_min_i32 s14, s14, 8
	v_ashrrev_i16_sdwa v1, v2, sext(v1) dst_sel:DWORD dst_unused:UNUSED_PAD src0_sel:DWORD src1_sel:BYTE_0
	s_abs_i32 s15, s14
	v_bfe_i32 v14, v1, 0, 16
	v_cvt_f32_u32_e32 v1, s15
	v_lshlrev_b32_e32 v4, 5, v13
	v_and_b32_e32 v4, 32, v4
	v_add_lshl_u32 v2, v4, v14, 1
	v_lshl_add_u32 v132, v0, 11, v2
	v_rcp_iflag_f32_e32 v0, v1
	s_sub_i32 s17, 0, s15
	s_and_b32 s1, s1, 0xffffff80
	s_sub_i32 s0, s0, s1
	v_mul_f32_e32 v0, 0x4f7ffffe, v0
	v_cvt_u32_f32_e32 v0, v0
	s_abs_i32 s16, s0
	s_xor_b32 s1, s0, s14
	s_ashr_i32 s1, s1, 31
	v_readfirstlane_b32 s18, v0
	s_mul_i32 s17, s17, s18
	s_mul_hi_u32 s17, s18, s17
	s_add_i32 s18, s18, s17
	s_mul_hi_u32 s17, s16, s18
	s_mul_i32 s18, s17, s15
	s_sub_i32 s16, s16, s18
	s_add_i32 s18, s17, 1
	s_sub_i32 s19, s16, s15
	s_cmp_ge_u32 s16, s15
	s_cselect_b32 s17, s18, s17
	s_cselect_b32 s16, s19, s16
	s_add_i32 s18, s17, 1
	s_cmp_ge_u32 s16, s15
	s_cselect_b32 s15, s18, s17
	s_xor_b32 s15, s15, s1
	s_sub_i32 s34, s15, s1
	s_mul_i32 s1, s34, s14
	s_sub_i32 s0, s0, s1
	s_add_i32 s36, s13, s0
	s_sub_i32 s34, 15, s34
	s_ashr_i32 s37, s36, 31
	s_ashr_i32 s35, s34, 31
	s_lshl_b64 s[0:1], s[36:37], 19
	s_lshl_b64 s[14:15], s[34:35], 19
	s_add_u32 s40, s3, s14
	s_addc_u32 s41, s21, s15
	s_add_i32 s37, s67, 0
	s_add_i32 m0, s37, 0x10000
	v_lshl_add_u32 v134, v3, 11, v2
	global_load_lds_dwordx4 v132, s[40:41]
	s_add_i32 m0, s37, 0x12000
	s_add_u32 s14, s40, 0x10000
	global_load_lds_dwordx4 v128, s[40:41]
	s_addc_u32 s15, s41, 0
	s_add_i32 m0, s37, 0x14000
	v_mov_b32_e32 v137, 0
	global_load_lds_dwordx4 v132, s[14:15]
	s_add_i32 m0, s37, 0x16000
	s_add_u32 s38, s8, s0
	s_addc_u32 s39, s9, s1
	s_add_i32 s46, s37, 0x2000
	global_load_lds_dwordx4 v128, s[14:15]
	s_mov_b32 m0, s37
	s_add_u32 s0, s38, 0x40000
	global_load_lds_dwordx4 v134, s[38:39]
	s_mov_b32 m0, s46
	s_addc_u32 s1, s39, 0
	s_add_i32 s47, s37, 0x4000
	global_load_lds_dwordx4 v130, s[38:39]
	s_mov_b32 m0, s47
	s_add_i32 s50, s37, 0x6000
	global_load_lds_dwordx4 v134, s[0:1]
	s_mov_b32 m0, s50
	v_mov_b32_e32 v133, v137
	global_load_lds_dwordx4 v130, s[0:1]
	v_readlane_b32 s0, v255, 17
	v_mov_b32_e32 v129, v137
	v_mov_b32_e32 v135, v137
	v_mov_b32_e32 v131, v137
	s_cmp_eq_u32 s0, 1
	s_mov_b32 s13, 0
	v_lshl_add_u64 v[4:5], s[40:41], 0, v[132:133]
	v_lshl_add_u64 v[2:3], s[40:41], 0, v[128:129]
	v_lshl_add_u64 v[0:1], s[38:39], 0, v[134:135]
	s_cselect_b64 s[14:15], -1, 0
	s_cmp_lg_u32 s0, 1
	v_lshl_add_u64 v[6:7], s[38:39], 0, v[130:131]
	s_cbranch_scc1 .LBB0_971
	s_barrier

;     __host__ __device__ bool next(int i, Unit& u) const { return at((long)i * G + c, u); }
;     __host__ __device__ bool next(int i, Unit& u) const { if (i != 0 || c >= cnt) return false; u.pm = pm0 + c / nN; u.pn = c % nN; u.k0 = 0; u.nt = ntk; return true; }
;     __host__ __device__ bool at(long L, Unit& u) const {
;         if (L >= nwg) return false;
;         int wgid = (int)L; { const int q = nwg / NXCD, r = nwg % NXCD, xcd = wgid % NXCD, off = wgid / NXCD; wgid = (xcd < r ? xcd * (q + 1) : r * (q + 1) + (xcd - r) * q) + off; }
;         const int nig = WGM * nN, gid = wgid / nig, fm = gid * WGM, gsz = (nM - fm) < WGM ? (nM - fm) : WGM;
;         u.pm = fm + ((wgid % nig) % gsz); u.pn = (wgid % nig) / gsz; u.k0 = 0; u.nt = ntk; return true;
;     ...
;         const bool has_next = S.next(ui + 1, nxt);
;         const char* nA = has_next ? (const char*)g.A + (size_t)nxt.pm * tstep + (size_t)nxt.k0 * (BK * 2) : cA; const char* nB = has_next ? (const char*)g.Bt + (size_t)nxt.pn * tstep + (size_t)nxt.k0 * (BK * 2) : cB;
.LBB0_974:
	s_add_i32 s57, s57, 1
	s_mul_i32 s0, s57, s53
	s_mul_hi_u32 s1, s57, s96
	s_add_i32 s1, s1, s0
	s_mul_i32 s0, s57, s96
	s_add_u32 s28, s0, s2
	s_addc_u32 s29, s1, s44
	v_cmp_ge_i64_e32 vcc, s[28:29], v[142:143]
	v_cmp_lt_i64_e64 s[0:1], s[28:29], v[142:143]
	s_cbranch_vccnz .LBB0_976
	s_ashr_i32 s24, s28, 31
	s_lshr_b32 s24, s24, 29
	s_add_i32 s24, s28, s24
	s_ashr_i32 s25, s24, 3
	s_and_b32 s24, s24, -8
	s_sub_i32 s24, s28, s24
	s_cmp_lt_i32 s24, 0
	s_cselect_b32 s26, s45, s23
	s_mul_i32 s24, s26, s24
	s_add_i32 s24, s24, s25
	s_ashr_i32 s25, s24, 31
	s_lshr_b32 s25, s25, 25
	s_add_i32 s25, s24, s25
	s_ashr_i32 s26, s25, 7
	s_lshl_b32 s26, s26, 3
	s_sub_i32 s27, s49, s26
	s_min_i32 s27, s27, 8
	s_abs_i32 s28, s27
	v_cvt_f32_u32_e32 v0, s28
	s_sub_i32 s30, 0, s28
	s_and_b32 s25, s25, 0xffffff80
	s_sub_i32 s25, s24, s25
	v_rcp_iflag_f32_e32 v0, v0
	s_abs_i32 s24, s25
	s_xor_b32 s29, s25, s27
	s_ashr_i32 s29, s29, 31
	v_mul_f32_e32 v0, 0x4f7ffffe, v0
	v_cvt_u32_f32_e32 v0, v0
	s_nop 0
	v_readfirstlane_b32 s31, v0
	s_mul_i32 s30, s30, s31
	s_mul_hi_u32 s30, s31, s30
	s_add_i32 s31, s31, s30
	s_mul_hi_u32 s30, s24, s31
	s_mul_i32 s31, s30, s28
	s_sub_i32 s24, s24, s31
	s_add_i32 s35, s30, 1
	s_sub_i32 s31, s24, s28
	s_cmp_ge_u32 s24, s28
	s_cselect_b32 s30, s35, s30
	s_cselect_b32 s24, s31, s24
	s_add_i32 s31, s30, 1
	s_cmp_ge_u32 s24, s28
	s_cselect_b32 s24, s31, s30
	s_xor_b32 s24, s24, s29
	s_sub_i32 s24, s24, s29
	s_mul_i32 s27, s24, s27
	s_sub_i32 s25, s25, s27
	s_add_i32 s26, s25, s26
	s_sub_i32 s24, 15, s24
